# accumulator zero-init in GEMM tile heads with 64-bit moves (half the instructions)
# speedup vs baseline: 1.1555x; 1.0027x over previous
.LBB0_36:
	v_bfe_i32 v1, v144, 27, 1
	s_waitcnt vmcnt(0)
	v_lshlrev_b32_e32 v14, 4, v144
	v_lshrrev_b32_e32 v1, 22, v1
	v_add_u32_e32 v1, v14, v1
	v_and_b32_e32 v1, 0xfffffc00, v1
	v_ashrrev_i32_e32 v0, 31, v144
	v_sub_u32_e32 v1, v14, v1
	v_lshrrev_b32_e32 v0, 26, v0
	v_lshrrev_b32_e32 v2, 4, v1
	v_add_u32_e32 v0, v144, v0
	v_bitop3_b32 v2, v2, v1, 32 bitop3:0x6c
	v_ashrrev_i32_e32 v1, 31, v1
	v_ashrrev_i32_e32 v0, 6, v0
	v_lshrrev_b32_e32 v1, 26, v1
	v_lshlrev_b32_e32 v3, 3, v0
	v_add_u32_e32 v1, v2, v1
	v_and_b32_e32 v3, -16, v3
	v_ashrrev_i32_e32 v1, 6, v1
	v_add_u32_e32 v12, v1, v3
	v_mul_i32_i24_e32 v1, 64, v1
	v_lshlrev_b32_e32 v0, 5, v0
	v_sub_u32_e32 v1, v2, v1
	v_mov_b32_e32 v5, 1
	v_and_b32_e32 v0, 32, v0
	v_ashrrev_i16_sdwa v1, v5, sext(v1) dst_sel:DWORD dst_unused:UNUSED_PAD src0_sel:DWORD src1_sel:BYTE_0
	s_add_i32 s0, s0, s1
	v_add_u32_sdwa v128, v0, sext(v1) dst_sel:DWORD dst_unused:UNUSED_PAD src0_sel:DWORD src1_sel:WORD_0
	v_add_u32_e32 v0, 0x2000, v14
	s_ashr_i32 s1, s0, 31
	v_ashrrev_i32_e32 v1, 31, v0
	s_lshr_b32 s1, s1, 28
	v_lshrrev_b32_e32 v1, 22, v1
	s_add_i32 s1, s0, s1
	v_add_u32_e32 v1, v0, v1
	s_and_b32 s2, s1, 0xfff0
	v_ashrrev_i32_e32 v1, 10, v1
	s_sub_i32 s0, s0, s2
	v_mul_i32_i24_e32 v2, 0x400, v1
	s_bfe_i32 s2, s0, 0x80000
	v_sub_u32_e32 v0, v0, v2
	s_bfe_u32 s2, s2, 0x2000d
	v_lshrrev_b32_e32 v2, 4, v0
	s_add_i32 s2, s0, s2
	v_bitop3_b32 v0, v2, v0, 32 bitop3:0x6c
	s_bfe_i32 s3, s2, 0x80000
	s_and_b32 s2, s2, 0xfc
	v_ashrrev_i32_e32 v3, 31, v0
	s_sext_i32_i16 s3, s3
	s_sub_i32 s0, s0, s2
	v_lshrrev_b32_e32 v3, 26, v3
	s_sext_i32_i8 s0, s0
	s_lshl_b32 s1, s1, 6
	s_ashr_i32 s22, s3, 2
	v_lshlrev_b32_e32 v2, 3, v1
	v_add_u32_e32 v3, v0, v3
	s_and_b32 s1, s1, 0xfffffc00
	s_lshl_b32 s23, s0, 8
	s_mul_i32 s0, s22, 0xb0000
	v_and_b32_e32 v2, -16, v2
	v_ashrrev_i32_e32 v4, 6, v3
	s_add_i32 s23, s23, s1
	s_ashr_i32 s1, s0, 31
	v_add_u32_e32 v13, v4, v2
	v_and_b32_e32 v2, 0xc0, v3
	s_lshl_b64 s[6:7], s[0:1], 1
	v_readlane_b32 s0, v254, 61
	s_movk_i32 s2, 0xb00
	v_lshlrev_b32_e32 v1, 5, v1
	v_sub_u32_e32 v0, v0, v2
	s_add_u32 s10, s18, s6
	v_add_u32_e32 v152, s0, v14
	v_mad_i64_i32 v[132:133], s[0:1], v12, s2, 0
	v_and_b32_e32 v1, 32, v1
	v_ashrrev_i16_sdwa v0, v5, sext(v0) dst_sel:DWORD dst_unused:UNUSED_PAD src0_sel:DWORD src1_sel:BYTE_0
	s_addc_u32 s11, s19, s7
	v_lshlrev_b64 v[16:17], 1, v[132:133]
	v_ashrrev_i32_e32 v129, 31, v128
	v_readfirstlane_b32 s0, v152
	v_add_u32_sdwa v130, v1, sext(v0) dst_sel:DWORD dst_unused:UNUSED_PAD src0_sel:DWORD src1_sel:WORD_0
	v_lshl_add_u64 v[2:3], s[10:11], 0, v[16:17]
	v_lshlrev_b64 v[0:1], 1, v[128:129]
	s_mov_b32 m0, s0
	v_mad_i64_i32 v[134:135], s[0:1], v13, s2, 0
	v_add_u32_e32 v153, 0x2000, v152
	v_lshl_add_u64 v[4:5], v[2:3], 0, v[0:1]
	v_readfirstlane_b32 s0, v153
	s_mul_i32 s8, s23, 0x1600
	global_load_lds_dwordx4 v[4:5], off
	v_lshlrev_b64 v[18:19], 1, v[134:135]
	v_ashrrev_i32_e32 v131, 31, v130
	s_mov_b32 m0, s0
	s_mul_hi_i32 s9, s23, 0x1600
	s_add_u32 s0, s66, s8
	v_lshl_add_u64 v[6:7], s[10:11], 0, v[18:19]
	v_lshlrev_b64 v[2:3], 1, v[130:131]
	s_addc_u32 s1, s67, s9
	v_add_u32_e32 v155, 0, v14
	v_lshl_add_u64 v[6:7], v[6:7], 0, v[2:3]
	v_lshl_add_u64 v[8:9], s[0:1], 0, v[16:17]
	v_readfirstlane_b32 s2, v155
	v_add_u32_e32 v156, 0x2000, v155
	global_load_lds_dwordx4 v[6:7], off
	v_lshl_add_u64 v[10:11], v[8:9], 0, v[0:1]
	s_mov_b32 m0, s2
	v_lshl_add_u64 v[8:9], s[0:1], 0, v[18:19]
	v_readfirstlane_b32 s0, v156
	global_load_lds_dwordx4 v[10:11], off
	s_mov_b32 m0, s0
	s_add_u32 s0, s10, 0xb0000
	v_readlane_b32 s2, v254, 62
	s_addc_u32 s1, s11, 0
	v_lshl_add_u64 v[8:9], v[8:9], 0, v[2:3]
	v_add_u32_e32 v157, s2, v14
	v_lshl_add_u64 v[20:21], s[0:1], 0, v[16:17]
	v_readfirstlane_b32 s2, v157
	global_load_lds_dwordx4 v[8:9], off
	v_lshl_add_u64 v[20:21], v[20:21], 0, v[0:1]
	s_mov_b32 m0, s2
	v_add_u32_e32 v159, 0x2000, v157
	global_load_lds_dwordx4 v[20:21], off
	v_lshl_add_u64 v[20:21], s[0:1], 0, v[18:19]
	v_readfirstlane_b32 s0, v159
	s_mov_b32 m0, s0
	s_or_b32 s0, s23, 0x80
	s_mul_hi_i32 s1, s0, 0xb00
	s_mulk_i32 s0, 0xb00
	s_lshl_b64 s[4:5], s[0:1], 1
	s_add_u32 s0, s66, s4
	s_addc_u32 s1, s67, s5
	v_add_u32_e32 v160, 0x4000, v155
	v_lshl_add_u64 v[20:21], v[20:21], 0, v[2:3]
	v_lshl_add_u64 v[16:17], s[0:1], 0, v[16:17]
	v_readfirstlane_b32 s2, v160
	global_load_lds_dwordx4 v[20:21], off
	v_lshl_add_u64 v[16:17], v[16:17], 0, v[0:1]
	s_mov_b32 m0, s2
	v_add_u32_e32 v164, 0x6000, v155
	global_load_lds_dwordx4 v[16:17], off
	v_lshl_add_u64 v[16:17], s[0:1], 0, v[18:19]
	v_readfirstlane_b32 s0, v164
	v_lshl_add_u64 v[16:17], v[16:17], 0, v[2:3]
	s_mov_b32 m0, s0
	v_ashrrev_i32_e32 v15, 8, v144
	global_load_lds_dwordx4 v[16:17], off
	v_mov_b32_e32 v21, 0
	v_mov_b64_e32 v[22:23], 0
	v_mov_b64_e32 v[24:25], 0
	v_mov_b64_e32 v[26:27], 0
	v_mov_b64_e32 v[28:29], 0
	v_mov_b64_e32 v[30:31], 0
	v_mov_b64_e32 v[32:33], 0
	v_mov_b64_e32 v[34:35], 0
	v_mov_b64_e32 v[36:37], 0
	v_mov_b64_e32 v[38:39], 0
	v_mov_b64_e32 v[40:41], 0
	v_mov_b64_e32 v[42:43], 0
	v_mov_b64_e32 v[44:45], 0
	v_mov_b64_e32 v[46:47], 0
	v_mov_b64_e32 v[48:49], 0
	v_mov_b64_e32 v[50:51], 0
	v_mov_b64_e32 v[52:53], 0
	v_mov_b64_e32 v[54:55], 0
	v_mov_b64_e32 v[56:57], 0
	v_mov_b64_e32 v[58:59], 0
	v_mov_b64_e32 v[60:61], 0
	v_mov_b64_e32 v[62:63], 0
	v_mov_b64_e32 v[64:65], 0
	v_mov_b64_e32 v[66:67], 0
	v_mov_b64_e32 v[68:69], 0
	v_mov_b64_e32 v[70:71], 0
	v_mov_b64_e32 v[72:73], 0
	v_mov_b64_e32 v[74:75], 0
	v_mov_b64_e32 v[76:77], 0
	v_mov_b64_e32 v[78:79], 0
	v_mov_b64_e32 v[80:81], 0
	v_mov_b64_e32 v[82:83], 0
	v_mov_b64_e32 v[84:85], 0
	v_mov_b64_e32 v[86:87], 0
	v_mov_b64_e32 v[88:89], 0
	v_mov_b64_e32 v[90:91], 0
	v_mov_b64_e32 v[92:93], 0
	v_mov_b64_e32 v[94:95], 0
	v_mov_b64_e32 v[96:97], 0
	v_mov_b64_e32 v[98:99], 0
	v_mov_b64_e32 v[100:101], 0
	v_mov_b64_e32 v[102:103], 0
	v_mov_b64_e32 v[104:105], 0
	v_mov_b64_e32 v[106:107], 0
	v_mov_b64_e32 v[108:109], 0
	v_mov_b64_e32 v[110:111], 0
	v_mov_b64_e32 v[112:113], 0
	v_mov_b64_e32 v[114:115], 0
	v_mov_b64_e32 v[116:117], 0
	v_mov_b64_e32 v[118:119], 0
	v_mov_b64_e32 v[120:121], 0
	v_mov_b64_e32 v[122:123], 0
	v_mov_b64_e32 v[124:125], 0
	v_mov_b64_e32 v[126:127], 0
	v_not_b32_e32 v246, 63
	v_cmp_eq_u32_e32 vcc, 1, v15
	s_and_saveexec_b64 s[12:13], vcc
	s_cbranch_execz .LBB0_38
	s_barrier

.LBB0_47:
	v_mbcnt_lo_u32_b32 v0, -1, 0
	v_mbcnt_hi_u32_b32 v0, -1, v0
	s_ashr_i32 s0, s13, 31
	v_add_u32_e32 v140, s48, v0
	s_lshr_b32 s0, s0, 29
	v_ashrrev_i32_e32 v0, 31, v140
	v_lshrrev_b32_e32 v0, 26, v0
	v_add_u32_e32 v0, v140, v0
	v_ashrrev_i32_e32 v1, 6, v0
	v_bfe_i32 v0, v140, 27, 1
	v_lshlrev_b32_e32 v21, 4, v140
	v_lshrrev_b32_e32 v0, 22, v0
	v_add_u32_e32 v0, v21, v0
	v_and_b32_e32 v0, 0xfffffc00, v0
	v_sub_u32_e32 v0, v21, v0
	v_lshrrev_b32_e32 v2, 4, v0
	s_add_i32 s0, s13, s0
	v_bitop3_b32 v2, v2, v0, 32 bitop3:0x6c
	v_ashrrev_i32_e32 v0, 31, v0
	s_ashr_i32 s1, s0, 3
	s_and_b32 s0, s0, -8
	v_lshrrev_b32_e32 v0, 26, v0
	s_sub_i32 s0, s13, s0
	v_lshlrev_b32_e32 v3, 3, v1
	v_add_u32_e32 v0, v2, v0
	s_cmp_lt_i32 s0, 0
	s_movk_i32 s2, 0xb1
	v_and_b32_e32 v3, -16, v3
	s_waitcnt vmcnt(0)
	v_ashrrev_i32_e32 v4, 6, v0
	s_cselect_b32 s2, s2, 0xb0
	v_add_u32_e32 v0, v4, v3
	v_mul_i32_i24_e32 v3, 64, v4
	s_mul_i32 s0, s2, s0
	v_lshlrev_b32_e32 v1, 5, v1
	v_sub_u32_e32 v2, v2, v3
	v_mov_b32_e32 v7, 1
	s_add_i32 s0, s0, s1
	v_and_b32_e32 v1, 32, v1
	v_ashrrev_i16_sdwa v2, v7, sext(v2) dst_sel:DWORD dst_unused:UNUSED_PAD src0_sel:DWORD src1_sel:BYTE_0
	s_mul_hi_i32 s1, s0, 0x2e8ba2e9
	v_add_u32_sdwa v2, v1, sext(v2) dst_sel:DWORD dst_unused:UNUSED_PAD src0_sel:DWORD src1_sel:WORD_0
	v_add_u32_e32 v1, 0x2000, v21
	s_lshr_b32 s2, s1, 31
	s_ashr_i32 s1, s1, 4
	v_ashrrev_i32_e32 v3, 31, v1
	s_add_i32 s1, s1, s2
	v_lshrrev_b32_e32 v3, 22, v3
	s_mul_i32 s2, s1, 0x58
	v_add_u32_e32 v3, v1, v3
	s_sub_i32 s0, s0, s2
	v_ashrrev_i32_e32 v3, 10, v3
	s_bfe_i32 s2, s0, 0x80000
	v_mul_i32_i24_e32 v4, 0x400, v3
	s_bfe_u32 s2, s2, 0x2000d
	v_sub_u32_e32 v1, v1, v4
	s_add_i32 s2, s0, s2
	v_lshrrev_b32_e32 v4, 4, v1
	s_bfe_i32 s3, s2, 0x80000
	s_and_b32 s2, s2, 0xfc
	v_bitop3_b32 v1, v4, v1, 32 bitop3:0x6c
	s_sub_i32 s0, s0, s2
	v_ashrrev_i32_e32 v5, 31, v1
	s_sext_i32_i16 s3, s3
	s_sext_i32_i8 s0, s0
	v_lshrrev_b32_e32 v5, 26, v5
	s_lshl_b32 s1, s1, 10
	s_lshl_b32 s0, s0, 8
	s_ashr_i32 s16, s3, 2
	v_add_u32_e32 v5, v1, v5
	s_add_i32 s4, s0, s1
	s_lshl_b32 s0, s16, 8
	v_lshlrev_b32_e32 v4, 3, v3
	v_ashrrev_i32_e32 v6, 6, v5
	v_and_b32_e32 v5, 0xc0, v5
	s_ashr_i32 s1, s0, 31
	v_and_b32_e32 v4, -16, v4
	v_lshlrev_b32_e32 v3, 5, v3
	v_sub_u32_e32 v1, v1, v5
	s_lshl_b64 s[6:7], s[0:1], 11
	v_add_u32_e32 v4, v6, v4
	v_and_b32_e32 v3, 32, v3
	v_ashrrev_i16_sdwa v1, v7, sext(v1) dst_sel:DWORD dst_unused:UNUSED_PAD src0_sel:DWORD src1_sel:BYTE_0
	s_add_u32 s2, s14, s6
	v_add_u32_sdwa v6, v3, sext(v1) dst_sel:DWORD dst_unused:UNUSED_PAD src0_sel:DWORD src1_sel:WORD_0
	s_addc_u32 s3, s15, s7
	v_readlane_b32 s1, v254, 61
	v_ashrrev_i32_e32 v1, 31, v0
	v_ashrrev_i32_e32 v5, 31, v4
	s_ashr_i32 s5, s4, 31
	v_add_u32_e32 v144, s1, v21
	v_lshlrev_b64 v[0:1], 11, v[0:1]
	v_ashrrev_i32_e32 v3, 31, v2
	v_lshlrev_b64 v[4:5], 11, v[4:5]
	s_lshl_b64 s[8:9], s[4:5], 11
	v_lshl_add_u64 v[8:9], s[2:3], 0, v[0:1]
	v_lshlrev_b64 v[2:3], 1, v[2:3]
	v_readfirstlane_b32 s1, v144
	v_lshl_add_u64 v[10:11], s[2:3], 0, v[4:5]
	v_ashrrev_i32_e32 v7, 31, v6
	v_add_u32_e32 v149, 0x2000, v144
	s_add_u32 s2, s44, s8
	v_lshl_add_u64 v[8:9], v[8:9], 0, v[2:3]
	s_mov_b32 m0, s1
	v_lshlrev_b64 v[6:7], 1, v[6:7]
	v_readfirstlane_b32 s1, v149
	s_addc_u32 s3, s45, s9
	v_add_u32_e32 v151, 0, v21
	global_load_lds_dwordx4 v[8:9], off
	v_lshl_add_u64 v[10:11], v[10:11], 0, v[6:7]
	s_mov_b32 m0, s1
	v_lshl_add_u64 v[12:13], s[2:3], 0, v[0:1]
	v_readfirstlane_b32 s1, v151
	v_add_u32_e32 v152, 0x2000, v151
	global_load_lds_dwordx4 v[10:11], off
	v_lshl_add_u64 v[12:13], v[12:13], 0, v[2:3]
	s_mov_b32 m0, s1
	v_readfirstlane_b32 s1, v152
	s_bitset1_b32 s0, 7
	global_load_lds_dwordx4 v[12:13], off
	s_mov_b32 m0, s1
	s_ashr_i32 s1, s0, 31
	s_lshl_b64 s[0:1], s[0:1], 11
	v_lshl_add_u64 v[14:15], s[2:3], 0, v[4:5]
	s_add_u32 s0, s14, s0
	v_readlane_b32 s2, v254, 62
	s_addc_u32 s1, s15, s1
	v_lshl_add_u64 v[14:15], v[14:15], 0, v[6:7]
	v_add_u32_e32 v153, s2, v21
	v_lshl_add_u64 v[16:17], s[0:1], 0, v[0:1]
	v_readfirstlane_b32 s2, v153
	v_add_u32_e32 v154, 0x2000, v153
	global_load_lds_dwordx4 v[14:15], off
	v_lshl_add_u64 v[16:17], v[16:17], 0, v[2:3]
	s_mov_b32 m0, s2
	v_lshl_add_u64 v[18:19], s[0:1], 0, v[4:5]
	v_readfirstlane_b32 s0, v154
	global_load_lds_dwordx4 v[16:17], off
	s_mov_b32 m0, s0
	s_or_b32 s0, s4, 0x80
	s_ashr_i32 s1, s0, 31
	s_lshl_b64 s[0:1], s[0:1], 11
	s_add_u32 s0, s44, s0
	s_addc_u32 s1, s45, s1
	v_add_u32_e32 v156, 0x4000, v151
	v_lshl_add_u64 v[18:19], v[18:19], 0, v[6:7]
	v_lshl_add_u64 v[22:23], s[0:1], 0, v[0:1]
	v_readfirstlane_b32 s2, v156
	v_add_u32_e32 v157, 0x6000, v151
	global_load_lds_dwordx4 v[18:19], off
	v_lshl_add_u64 v[128:129], v[22:23], 0, v[2:3]
	s_mov_b32 m0, s2
	v_lshl_add_u64 v[22:23], s[0:1], 0, v[4:5]
	v_readfirstlane_b32 s0, v157
	global_load_lds_dwordx4 v[128:129], off
	v_lshl_add_u64 v[130:131], v[22:23], 0, v[6:7]
	s_mov_b32 m0, s0
	v_ashrrev_i32_e32 v20, 8, v140
	global_load_lds_dwordx4 v[130:131], off
	v_mov_b32_e32 v23, 0
	v_mov_b64_e32 v[24:25], 0
	v_mov_b64_e32 v[26:27], 0
	v_mov_b64_e32 v[28:29], 0
	v_mov_b64_e32 v[30:31], 0
	v_mov_b64_e32 v[32:33], 0
	v_mov_b64_e32 v[34:35], 0
	v_mov_b64_e32 v[36:37], 0
	v_mov_b64_e32 v[38:39], 0
	v_mov_b64_e32 v[40:41], 0
	v_mov_b64_e32 v[42:43], 0
	v_mov_b64_e32 v[44:45], 0
	v_mov_b64_e32 v[46:47], 0
	v_mov_b64_e32 v[48:49], 0
	v_mov_b64_e32 v[50:51], 0
	v_mov_b64_e32 v[52:53], 0
	v_mov_b64_e32 v[54:55], 0
	v_mov_b64_e32 v[56:57], 0
	v_mov_b64_e32 v[58:59], 0
	v_mov_b64_e32 v[60:61], 0
	v_mov_b64_e32 v[62:63], 0
	v_mov_b64_e32 v[64:65], 0
	v_mov_b64_e32 v[66:67], 0
	v_mov_b64_e32 v[68:69], 0
	v_mov_b64_e32 v[70:71], 0
	v_mov_b64_e32 v[72:73], 0
	v_mov_b64_e32 v[74:75], 0
	v_mov_b64_e32 v[76:77], 0
	v_mov_b64_e32 v[78:79], 0
	v_mov_b64_e32 v[80:81], 0
	v_mov_b64_e32 v[82:83], 0
	v_mov_b64_e32 v[84:85], 0
	v_mov_b64_e32 v[86:87], 0
	v_mov_b64_e32 v[88:89], 0
	v_mov_b64_e32 v[90:91], 0
	v_mov_b64_e32 v[92:93], 0
	v_mov_b64_e32 v[94:95], 0
	v_mov_b64_e32 v[96:97], 0
	v_mov_b64_e32 v[98:99], 0
	v_mov_b64_e32 v[100:101], 0
	v_mov_b64_e32 v[102:103], 0
	v_mov_b64_e32 v[104:105], 0
	v_mov_b64_e32 v[106:107], 0
	v_mov_b64_e32 v[108:109], 0
	v_mov_b64_e32 v[110:111], 0
	v_mov_b64_e32 v[112:113], 0
	v_mov_b64_e32 v[114:115], 0
	v_mov_b64_e32 v[116:117], 0
	v_mov_b64_e32 v[118:119], 0
	v_mov_b64_e32 v[120:121], 0
	v_mov_b64_e32 v[122:123], 0
	v_mov_b64_e32 v[124:125], 0
	v_mov_b64_e32 v[126:127], 0
	v_cmp_eq_u32_e32 vcc, 1, v20
	s_and_saveexec_b64 s[10:11], vcc
	s_cbranch_execz .LBB0_49
	s_barrier

.LBB0_68:
	v_bfe_i32 v1, v144, 27, 1
	v_lshlrev_b32_e32 v24, 4, v144
	v_lshrrev_b32_e32 v1, 22, v1
	v_add_u32_e32 v1, v24, v1
	v_and_b32_e32 v1, 0xfffffc00, v1
	v_ashrrev_i32_e32 v0, 31, v144
	v_sub_u32_e32 v1, v24, v1
	v_lshrrev_b32_e32 v0, 26, v0
	v_lshrrev_b32_e32 v2, 4, v1
	v_add_u32_e32 v0, v144, v0
	v_bitop3_b32 v2, v2, v1, 32 bitop3:0x6c
	v_ashrrev_i32_e32 v1, 31, v1
	v_ashrrev_i32_e32 v0, 6, v0
	v_lshrrev_b32_e32 v1, 26, v1
	v_lshlrev_b32_e32 v3, 3, v0
	v_add_u32_e32 v1, v2, v1
	v_and_b32_e32 v3, -16, v3
	v_ashrrev_i32_e32 v1, 6, v1
	s_waitcnt vmcnt(0)
	v_add_u32_e32 v4, v1, v3
	v_mul_i32_i24_e32 v1, 64, v1
	v_lshlrev_b32_e32 v0, 5, v0
	v_sub_u32_e32 v1, v2, v1
	v_mov_b32_e32 v6, 1
	s_add_i32 s0, s0, s1
	v_and_b32_e32 v0, 32, v0
	v_ashrrev_i16_sdwa v1, v6, sext(v1) dst_sel:DWORD dst_unused:UNUSED_PAD src0_sel:DWORD src1_sel:BYTE_0
	s_ashr_i32 s1, s0, 31
	v_add_u32_sdwa v128, v0, sext(v1) dst_sel:DWORD dst_unused:UNUSED_PAD src0_sel:DWORD src1_sel:WORD_0
	v_add_u32_e32 v0, 0x2000, v24
	s_lshr_b32 s1, s1, 28
	v_ashrrev_i32_e32 v1, 31, v0
	s_add_i32 s1, s0, s1
	v_lshrrev_b32_e32 v1, 22, v1
	s_and_b32 s2, s1, 0xfff0
	v_add_u32_e32 v1, v0, v1
	s_sub_i32 s0, s0, s2
	v_ashrrev_i32_e32 v1, 10, v1
	s_bfe_i32 s2, s0, 0x80000
	v_mul_i32_i24_e32 v2, 0x400, v1
	s_bfe_u32 s2, s2, 0x2000d
	v_sub_u32_e32 v0, v0, v2
	s_add_i32 s2, s0, s2
	v_lshrrev_b32_e32 v2, 4, v0
	s_bfe_i32 s3, s2, 0x80000
	s_and_b32 s2, s2, 0xfc
	v_bitop3_b32 v0, v2, v0, 32 bitop3:0x6c
	s_sub_i32 s0, s0, s2
	v_ashrrev_i32_e32 v3, 31, v0
	s_sext_i32_i8 s0, s0
	s_lshl_b32 s1, s1, 6
	v_lshrrev_b32_e32 v3, 26, v3
	s_sext_i32_i16 s3, s3
	s_and_b32 s1, s1, 0xfffffc00
	s_lshl_b32 s0, s0, 8
	v_lshlrev_b32_e32 v2, 3, v1
	v_add_u32_e32 v3, v0, v3
	s_add_i32 s6, s0, s1
	s_lshl_b32 s0, s3, 6
	v_and_b32_e32 v2, -16, v2
	v_ashrrev_i32_e32 v5, 6, v3
	s_and_b32 s4, s0, 0xffffff00
	v_add_u32_e32 v10, v5, v2
	v_and_b32_e32 v2, 0xc0, v3
	s_ashr_i32 s5, s4, 31
	v_lshlrev_b32_e32 v1, 5, v1
	v_sub_u32_e32 v0, v0, v2
	s_lshl_b64 s[10:11], s[4:5], 11
	v_and_b32_e32 v1, 32, v1
	v_ashrrev_i16_sdwa v0, v6, sext(v0) dst_sel:DWORD dst_unused:UNUSED_PAD src0_sel:DWORD src1_sel:BYTE_0
	s_add_u32 s0, s22, s10
	v_ashrrev_i32_e32 v5, 31, v4
	v_add_u32_sdwa v130, v1, sext(v0) dst_sel:DWORD dst_unused:UNUSED_PAD src0_sel:DWORD src1_sel:WORD_0
	s_addc_u32 s1, s23, s11
	v_readlane_b32 s2, v254, 61
	v_lshlrev_b64 v[0:1], 11, v[4:5]
	v_ashrrev_i32_e32 v129, 31, v128
	v_add_u32_e32 v152, s2, v24
	v_lshl_add_u64 v[6:7], s[0:1], 0, v[0:1]
	v_lshlrev_b64 v[2:3], 1, v[128:129]
	v_ashrrev_i32_e32 v11, 31, v10
	v_lshl_add_u64 v[12:13], v[6:7], 0, v[2:3]
	v_readfirstlane_b32 s2, v152
	v_lshlrev_b64 v[6:7], 11, v[10:11]
	v_add_u32_e32 v154, 0x2000, v152
	s_ashr_i32 s7, s6, 31
	s_mov_b32 m0, s2
	v_lshl_add_u64 v[14:15], s[0:1], 0, v[6:7]
	v_readfirstlane_b32 s0, v154
	s_lshl_b64 s[12:13], s[6:7], 11
	global_load_lds_dwordx4 v[12:13], off
	v_ashrrev_i32_e32 v131, 31, v130
	s_mov_b32 m0, s0
	s_add_u32 s0, s20, s12
	v_lshlrev_b64 v[8:9], 1, v[130:131]
	s_addc_u32 s1, s21, s13
	v_add_u32_e32 v155, 0, v24
	v_lshl_add_u64 v[14:15], v[14:15], 0, v[8:9]
	v_lshl_add_u64 v[16:17], s[0:1], 0, v[0:1]
	v_readfirstlane_b32 s2, v155
	v_add_u32_e32 v156, 0x2000, v155
	global_load_lds_dwordx4 v[14:15], off
	v_lshl_add_u64 v[16:17], v[16:17], 0, v[2:3]
	s_mov_b32 m0, s2
	v_lshl_add_u64 v[18:19], s[0:1], 0, v[6:7]
	v_readfirstlane_b32 s0, v156
	global_load_lds_dwordx4 v[16:17], off
	s_mov_b32 m0, s0
	s_or_b32 s0, s4, 0x80
	s_ashr_i32 s1, s0, 31
	s_lshl_b64 s[0:1], s[0:1], 11
	s_add_u32 s0, s22, s0
	v_readlane_b32 s2, v254, 62
	s_addc_u32 s1, s23, s1
	v_lshl_add_u64 v[18:19], v[18:19], 0, v[8:9]
	v_add_u32_e32 v158, s2, v24
	v_lshl_add_u64 v[20:21], s[0:1], 0, v[0:1]
	v_readfirstlane_b32 s2, v158
	v_add_u32_e32 v159, 0x2000, v158
	s_or_b32 s8, s6, 0x80
	global_load_lds_dwordx4 v[18:19], off
	v_lshl_add_u64 v[20:21], v[20:21], 0, v[2:3]
	s_mov_b32 m0, s2
	v_lshl_add_u64 v[22:23], s[0:1], 0, v[6:7]
	v_readfirstlane_b32 s0, v159
	s_ashr_i32 s9, s8, 31
	global_load_lds_dwordx4 v[20:21], off
	s_mov_b32 m0, s0
	s_lshl_b64 s[0:1], s[8:9], 11
	s_add_u32 s0, s20, s0
	s_addc_u32 s1, s21, s1
	v_add_u32_e32 v160, 0x4000, v155
	v_lshl_add_u64 v[22:23], v[22:23], 0, v[8:9]
	v_lshl_add_u64 v[26:27], s[0:1], 0, v[0:1]
	v_readfirstlane_b32 s2, v160
	global_load_lds_dwordx4 v[22:23], off
	v_lshl_add_u64 v[26:27], v[26:27], 0, v[2:3]
	s_mov_b32 m0, s2
	v_add_u32_e32 v164, 0x6000, v155
	global_load_lds_dwordx4 v[26:27], off
	v_lshl_add_u64 v[26:27], s[0:1], 0, v[6:7]
	v_readfirstlane_b32 s0, v164
	v_lshl_add_u64 v[26:27], v[26:27], 0, v[8:9]
	s_mov_b32 m0, s0
	v_ashrrev_i32_e32 v25, 8, v144
	global_load_lds_dwordx4 v[26:27], off
	v_mov_b64_e32 v[26:27], 0
	v_mov_b64_e32 v[28:29], 0
	v_mov_b64_e32 v[30:31], 0
	v_mov_b64_e32 v[32:33], 0
	v_mov_b64_e32 v[34:35], 0
	v_mov_b64_e32 v[36:37], 0
	v_mov_b64_e32 v[38:39], 0
	v_mov_b64_e32 v[40:41], 0
	v_mov_b64_e32 v[42:43], 0
	v_mov_b64_e32 v[44:45], 0
	v_mov_b64_e32 v[46:47], 0
	v_mov_b64_e32 v[48:49], 0
	v_mov_b64_e32 v[50:51], 0
	v_mov_b64_e32 v[52:53], 0
	v_mov_b64_e32 v[54:55], 0
	v_mov_b64_e32 v[56:57], 0
	v_mov_b64_e32 v[58:59], 0
	v_mov_b64_e32 v[60:61], 0
	v_mov_b64_e32 v[62:63], 0
	v_mov_b64_e32 v[64:65], 0
	v_mov_b64_e32 v[66:67], 0
	v_mov_b64_e32 v[68:69], 0
	v_mov_b64_e32 v[70:71], 0
	v_mov_b64_e32 v[72:73], 0
	v_mov_b64_e32 v[74:75], 0
	v_mov_b64_e32 v[76:77], 0
	v_mov_b64_e32 v[78:79], 0
	v_mov_b64_e32 v[80:81], 0
	v_mov_b64_e32 v[82:83], 0
	v_mov_b64_e32 v[84:85], 0
	v_mov_b64_e32 v[86:87], 0
	v_mov_b64_e32 v[88:89], 0
	v_mov_b64_e32 v[90:91], 0
	v_mov_b64_e32 v[92:93], 0
	v_mov_b64_e32 v[94:95], 0
	v_mov_b64_e32 v[96:97], 0
	v_mov_b64_e32 v[98:99], 0
	v_mov_b64_e32 v[100:101], 0
	v_mov_b64_e32 v[102:103], 0
	v_mov_b64_e32 v[104:105], 0
	v_mov_b64_e32 v[106:107], 0
	v_mov_b64_e32 v[108:109], 0
	v_mov_b64_e32 v[110:111], 0
	v_mov_b64_e32 v[112:113], 0
	v_mov_b64_e32 v[114:115], 0
	v_mov_b64_e32 v[116:117], 0
	v_mov_b64_e32 v[118:119], 0
	v_mov_b64_e32 v[120:121], 0
	v_mov_b64_e32 v[122:123], 0
	v_mov_b64_e32 v[124:125], 0
	v_mov_b64_e32 v[126:127], 0
	v_cmp_eq_u32_e32 vcc, 1, v25
	s_and_saveexec_b64 s[14:15], vcc
	s_cbranch_execz .LBB0_70
	s_barrier

.LBB0_113:
	v_ashrrev_i32_e32 v0, 31, v140
	v_lshrrev_b32_e32 v0, 26, v0
	v_add_u32_e32 v0, v140, v0
	v_ashrrev_i32_e32 v1, 6, v0
	v_bfe_i32 v0, v140, 27, 1
	v_lshlrev_b32_e32 v21, 4, v140
	v_lshrrev_b32_e32 v0, 22, v0
	v_add_u32_e32 v0, v21, v0
	v_and_b32_e32 v0, 0xfffffc00, v0
	v_sub_u32_e32 v0, v21, v0
	v_lshrrev_b32_e32 v2, 4, v0
	v_bitop3_b32 v2, v2, v0, 32 bitop3:0x6c
	v_ashrrev_i32_e32 v0, 31, v0
	v_lshrrev_b32_e32 v0, 26, v0
	v_lshlrev_b32_e32 v3, 3, v1
	v_add_u32_e32 v0, v2, v0
	v_and_b32_e32 v3, -16, v3
	s_waitcnt vmcnt(0)
	v_ashrrev_i32_e32 v4, 6, v0
	v_add_u32_e32 v0, v4, v3
	v_mul_i32_i24_e32 v3, 64, v4
	v_lshlrev_b32_e32 v1, 5, v1
	v_sub_u32_e32 v2, v2, v3
	v_mov_b32_e32 v7, 1
	v_and_b32_e32 v1, 32, v1
	v_ashrrev_i16_sdwa v2, v7, sext(v2) dst_sel:DWORD dst_unused:UNUSED_PAD src0_sel:DWORD src1_sel:BYTE_0
	v_add_u32_sdwa v2, v1, sext(v2) dst_sel:DWORD dst_unused:UNUSED_PAD src0_sel:DWORD src1_sel:WORD_0
	v_add_u32_e32 v1, 0x2000, v21
	v_ashrrev_i32_e32 v3, 31, v1
	v_lshrrev_b32_e32 v3, 22, v3
	v_add_u32_e32 v3, v1, v3
	v_ashrrev_i32_e32 v3, 10, v3
	v_mul_i32_i24_e32 v4, 0x400, v3
	v_sub_u32_e32 v1, v1, v4
	v_lshrrev_b32_e32 v4, 4, v1
	v_bitop3_b32 v1, v4, v1, 32 bitop3:0x6c
	s_add_i32 s1, s0, s1
	v_ashrrev_i32_e32 v5, 31, v1
	s_mul_hi_i32 s0, s1, 0x2aaaaaab
	v_lshrrev_b32_e32 v5, 26, v5
	s_lshr_b32 s2, s0, 31
	s_ashr_i32 s0, s0, 2
	v_add_u32_e32 v5, v1, v5
	s_add_i32 s2, s0, s2
	v_ashrrev_i32_e32 v6, 6, v5
	v_and_b32_e32 v5, 0xc0, v5
	s_lshl_b32 s12, s2, 2
	v_lshlrev_b32_e32 v4, 3, v3
	v_lshlrev_b32_e32 v3, 5, v3
	v_sub_u32_e32 v1, v1, v5
	s_sub_i32 s0, 0x42, s12
	v_and_b32_e32 v4, -16, v4
	v_and_b32_e32 v3, 32, v3
	v_ashrrev_i16_sdwa v1, v7, sext(v1) dst_sel:DWORD dst_unused:UNUSED_PAD src0_sel:DWORD src1_sel:BYTE_0
	s_min_u32 s13, s0, 4
	s_mul_i32 s3, s2, 24
	v_add_u32_e32 v4, v6, v4
	v_add_u32_sdwa v6, v3, sext(v1) dst_sel:DWORD dst_unused:UNUSED_PAD src0_sel:DWORD src1_sel:WORD_0
	s_sub_i32 s14, s1, s3
	v_cvt_f32_ubyte0_e32 v3, s13
	v_cvt_f32_i32_e32 v1, s14
	v_rcp_iflag_f32_e32 v5, v3
	s_ashr_i32 s0, s14, 30
	s_or_b32 s0, s0, 1
	v_ashrrev_i32_e32 v7, 31, v6
	v_mul_f32_e32 v5, v1, v5
	v_trunc_f32_e32 v5, v5
	v_fma_f32 v1, -v5, v3, v1
	v_cvt_i32_f32_e32 v5, v5
	v_cmp_ge_f32_e64 s[4:5], |v1|, v3
	s_and_b64 s[4:5], s[4:5], exec
	s_cselect_b32 s0, s0, 0
	v_readfirstlane_b32 s4, v5
	s_add_i32 s0, s4, s0
	s_mul_i32 s18, s0, s13
	s_sub_i32 s4, s14, s18
	s_sext_i32_i8 s4, s4
	s_sext_i32_i8 s5, s0
	s_add_i32 s12, s12, s4
	s_lshl_b32 s4, s12, 8
	s_lshl_b32 s12, s5, 8
	s_ashr_i32 s13, s12, 31
	s_lshl_b64 s[14:15], s[12:13], 11
	s_add_u32 s16, s22, s14
	v_readlane_b32 s5, v254, 61
	v_ashrrev_i32_e32 v1, 31, v0
	s_addc_u32 s17, s23, s15
	v_add_u32_e32 v143, s5, v21
	v_lshlrev_b64 v[0:1], 11, v[0:1]
	v_ashrrev_i32_e32 v3, 31, v2
	v_lshl_add_u64 v[8:9], s[16:17], 0, v[0:1]
	v_lshlrev_b64 v[2:3], 1, v[2:3]
	v_readfirstlane_b32 s5, v143
	v_add_u32_e32 v148, 0x2000, v143
	v_lshl_add_u64 v[8:9], v[8:9], 0, v[2:3]
	s_mov_b32 m0, s5
	v_ashrrev_i32_e32 v5, 31, v4
	v_readfirstlane_b32 s5, v148
	global_load_lds_dwordx4 v[8:9], off
	v_lshlrev_b64 v[4:5], 11, v[4:5]
	s_mov_b32 m0, s5
	s_ashr_i32 s5, s4, 31
	v_lshl_add_u64 v[10:11], s[16:17], 0, v[4:5]
	s_lshl_b64 s[16:17], s[4:5], 11
	s_add_u32 s16, s44, s16
	s_addc_u32 s17, s45, s17
	v_lshl_add_u64 v[12:13], s[16:17], 0, v[0:1]
	v_lshl_add_u64 v[14:15], s[16:17], 0, v[4:5]
	s_or_b32 s16, s12, 0x80
	s_ashr_i32 s17, s16, 31
	s_lshl_b64 s[16:17], s[16:17], 11
	v_lshlrev_b64 v[6:7], 1, v[6:7]
	v_add_u32_e32 v149, 0, v21
	s_add_u32 s16, s22, s16
	v_lshl_add_u64 v[10:11], v[10:11], 0, v[6:7]
	v_readfirstlane_b32 s5, v149
	v_add_u32_e32 v151, 0x2000, v149
	s_addc_u32 s17, s23, s17
	global_load_lds_dwordx4 v[10:11], off
	v_lshl_add_u64 v[12:13], v[12:13], 0, v[2:3]
	s_mov_b32 m0, s5
	v_readfirstlane_b32 s5, v151
	v_lshl_add_u64 v[16:17], s[16:17], 0, v[0:1]
	v_lshl_add_u64 v[18:19], s[16:17], 0, v[4:5]
	s_or_b32 s16, s4, 0x80
	global_load_lds_dwordx4 v[12:13], off
	s_mov_b32 m0, s5
	v_readlane_b32 s5, v254, 62
	s_ashr_i32 s17, s16, 31
	s_lshl_b64 s[16:17], s[16:17], 11
	v_add_u32_e32 v152, s5, v21
	v_lshl_add_u64 v[14:15], v[14:15], 0, v[6:7]
	v_readfirstlane_b32 s5, v152
	v_add_u32_e32 v153, 0x2000, v152
	s_add_u32 s16, s44, s16
	global_load_lds_dwordx4 v[14:15], off
	v_lshl_add_u64 v[16:17], v[16:17], 0, v[2:3]
	s_mov_b32 m0, s5
	v_readfirstlane_b32 s5, v153
	s_addc_u32 s17, s45, s17
	v_add_u32_e32 v155, 0x4000, v149
	global_load_lds_dwordx4 v[16:17], off
	v_lshl_add_u64 v[18:19], v[18:19], 0, v[6:7]
	s_mov_b32 m0, s5
	v_lshl_add_u64 v[22:23], s[16:17], 0, v[0:1]
	v_readfirstlane_b32 s5, v155
	v_add_u32_e32 v156, 0x6000, v149
	global_load_lds_dwordx4 v[18:19], off
	v_lshl_add_u64 v[128:129], v[22:23], 0, v[2:3]
	s_mov_b32 m0, s5
	v_lshl_add_u64 v[22:23], s[16:17], 0, v[4:5]
	v_readfirstlane_b32 s5, v156
	global_load_lds_dwordx4 v[128:129], off
	v_lshl_add_u64 v[130:131], v[22:23], 0, v[6:7]
	s_mov_b32 m0, s5
	v_ashrrev_i32_e32 v20, 8, v140
	global_load_lds_dwordx4 v[130:131], off
	v_mov_b32_e32 v23, 0
	v_mov_b64_e32 v[24:25], 0
	v_mov_b64_e32 v[26:27], 0
	v_mov_b64_e32 v[28:29], 0
	v_mov_b64_e32 v[30:31], 0
	v_mov_b64_e32 v[32:33], 0
	v_mov_b64_e32 v[34:35], 0
	v_mov_b64_e32 v[36:37], 0
	v_mov_b64_e32 v[38:39], 0
	v_mov_b64_e32 v[40:41], 0
	v_mov_b64_e32 v[42:43], 0
	v_mov_b64_e32 v[44:45], 0
	v_mov_b64_e32 v[46:47], 0
	v_mov_b64_e32 v[48:49], 0
	v_mov_b64_e32 v[50:51], 0
	v_mov_b64_e32 v[52:53], 0
	v_mov_b64_e32 v[54:55], 0
	v_mov_b64_e32 v[56:57], 0
	v_mov_b64_e32 v[58:59], 0
	v_mov_b64_e32 v[60:61], 0
	v_mov_b64_e32 v[62:63], 0
	v_mov_b64_e32 v[64:65], 0
	v_mov_b64_e32 v[66:67], 0
	v_mov_b64_e32 v[68:69], 0
	v_mov_b64_e32 v[70:71], 0
	v_mov_b64_e32 v[72:73], 0
	v_mov_b64_e32 v[74:75], 0
	v_mov_b64_e32 v[76:77], 0
	v_mov_b64_e32 v[78:79], 0
	v_mov_b64_e32 v[80:81], 0
	v_mov_b64_e32 v[82:83], 0
	v_mov_b64_e32 v[84:85], 0
	v_mov_b64_e32 v[86:87], 0
	v_mov_b64_e32 v[88:89], 0
	v_mov_b64_e32 v[90:91], 0
	v_mov_b64_e32 v[92:93], 0
	v_mov_b64_e32 v[94:95], 0
	v_mov_b64_e32 v[96:97], 0
	v_mov_b64_e32 v[98:99], 0
	v_mov_b64_e32 v[100:101], 0
	v_mov_b64_e32 v[102:103], 0
	v_mov_b64_e32 v[104:105], 0
	v_mov_b64_e32 v[106:107], 0
	v_mov_b64_e32 v[108:109], 0
	v_mov_b64_e32 v[110:111], 0
	v_mov_b64_e32 v[112:113], 0
	v_mov_b64_e32 v[114:115], 0
	v_mov_b64_e32 v[116:117], 0
	v_mov_b64_e32 v[118:119], 0
	v_mov_b64_e32 v[120:121], 0
	v_mov_b64_e32 v[122:123], 0
	v_mov_b64_e32 v[124:125], 0
	v_mov_b64_e32 v[126:127], 0
	v_cmp_eq_u32_e32 vcc, 1, v20
	s_and_saveexec_b64 s[16:17], vcc
	s_cbranch_execz .LBB0_115
	s_barrier

.LBB0_186:
	v_bfe_i32 v1, v144, 27, 1
	s_waitcnt vmcnt(0)
	v_lshlrev_b32_e32 v14, 4, v144
	v_lshrrev_b32_e32 v1, 22, v1
	v_add_u32_e32 v1, v14, v1
	v_and_b32_e32 v1, 0xfffffc00, v1
	v_ashrrev_i32_e32 v0, 31, v144
	v_sub_u32_e32 v1, v14, v1
	v_lshrrev_b32_e32 v0, 26, v0
	v_lshrrev_b32_e32 v2, 4, v1
	v_add_u32_e32 v0, v144, v0
	v_bitop3_b32 v2, v2, v1, 32 bitop3:0x6c
	v_ashrrev_i32_e32 v1, 31, v1
	v_ashrrev_i32_e32 v0, 6, v0
	v_lshrrev_b32_e32 v1, 26, v1
	v_lshlrev_b32_e32 v3, 3, v0
	v_add_u32_e32 v1, v2, v1
	v_and_b32_e32 v3, -16, v3
	v_ashrrev_i32_e32 v1, 6, v1
	v_add_u32_e32 v12, v1, v3
	v_mul_i32_i24_e32 v1, 64, v1
	v_lshlrev_b32_e32 v0, 5, v0
	v_sub_u32_e32 v1, v2, v1
	v_mov_b32_e32 v5, 1
	v_and_b32_e32 v0, 32, v0
	v_ashrrev_i16_sdwa v1, v5, sext(v1) dst_sel:DWORD dst_unused:UNUSED_PAD src0_sel:DWORD src1_sel:BYTE_0
	v_add_u32_sdwa v128, v0, sext(v1) dst_sel:DWORD dst_unused:UNUSED_PAD src0_sel:DWORD src1_sel:WORD_0
	v_add_u32_e32 v0, 0x2000, v14
	v_ashrrev_i32_e32 v1, 31, v0
	v_lshrrev_b32_e32 v1, 22, v1
	v_add_u32_e32 v1, v0, v1
	v_ashrrev_i32_e32 v1, 10, v1
	v_mul_i32_i24_e32 v2, 0x400, v1
	v_sub_u32_e32 v0, v0, v2
	v_lshrrev_b32_e32 v2, 4, v0
	v_bitop3_b32 v0, v2, v0, 32 bitop3:0x6c
	v_ashrrev_i32_e32 v3, 31, v0
	s_mul_i32 s2, s21, 0xb0000
	v_lshrrev_b32_e32 v3, 26, v3
	s_ashr_i32 s3, s2, 31
	v_lshlrev_b32_e32 v2, 3, v1
	v_add_u32_e32 v3, v0, v3
	s_lshl_b64 s[4:5], s[2:3], 1
	v_and_b32_e32 v2, -16, v2
	v_ashrrev_i32_e32 v4, 6, v3
	s_add_u32 s2, s16, s4
	v_add_u32_e32 v13, v4, v2
	v_and_b32_e32 v2, 0xc0, v3
	s_addc_u32 s3, s17, s5
	s_lshl_b32 s68, s8, 1
	s_movk_i32 s22, 0xb00
	v_lshlrev_b32_e32 v1, 5, v1
	v_sub_u32_e32 v0, v0, v2
	s_add_u32 s10, s2, s68
	v_readlane_b32 s1, v254, 61
	v_mad_i64_i32 v[132:133], s[8:9], v12, s22, 0
	v_and_b32_e32 v1, 32, v1
	v_ashrrev_i16_sdwa v0, v5, sext(v0) dst_sel:DWORD dst_unused:UNUSED_PAD src0_sel:DWORD src1_sel:BYTE_0
	s_addc_u32 s11, s3, 0
	v_add_u32_e32 v148, s1, v14
	v_lshlrev_b64 v[16:17], 1, v[132:133]
	v_ashrrev_i32_e32 v129, 31, v128
	v_add_u32_sdwa v130, v1, sext(v0) dst_sel:DWORD dst_unused:UNUSED_PAD src0_sel:DWORD src1_sel:WORD_0
	v_lshl_add_u64 v[2:3], s[10:11], 0, v[16:17]
	v_lshlrev_b64 v[0:1], 1, v[128:129]
	v_readfirstlane_b32 s1, v148
	v_mad_i64_i32 v[134:135], s[8:9], v13, s22, 0
	v_add_u32_e32 v153, 0x2000, v148
	v_lshl_add_u64 v[4:5], v[2:3], 0, v[0:1]
	s_mov_b32 m0, s1
	v_readfirstlane_b32 s1, v153
	s_mul_i32 s8, s20, 0x1600
	global_load_lds_dwordx4 v[4:5], off
	s_mov_b32 m0, s1
	s_mul_hi_i32 s9, s20, 0x1600
	s_add_u32 s1, s66, s8
	s_addc_u32 s23, s67, s9
	v_lshlrev_b64 v[18:19], 1, v[134:135]
	v_ashrrev_i32_e32 v131, 31, v130
	s_add_u32 s22, s1, s68
	v_lshl_add_u64 v[6:7], s[10:11], 0, v[18:19]
	v_lshlrev_b64 v[2:3], 1, v[130:131]
	s_addc_u32 s23, s23, 0
	v_add_u32_e32 v155, 0, v14
	v_lshl_add_u64 v[6:7], v[6:7], 0, v[2:3]
	v_lshl_add_u64 v[8:9], s[22:23], 0, v[16:17]
	v_readfirstlane_b32 s1, v155
	v_add_u32_e32 v156, 0x2000, v155
	global_load_lds_dwordx4 v[6:7], off
	v_lshl_add_u64 v[10:11], v[8:9], 0, v[0:1]
	s_mov_b32 m0, s1
	v_readfirstlane_b32 s1, v156
	global_load_lds_dwordx4 v[10:11], off
	s_mov_b32 m0, s1
	s_add_u32 s10, s10, 0xb0000
	v_readlane_b32 s1, v254, 62
	v_lshl_add_u64 v[8:9], s[22:23], 0, v[18:19]
	s_addc_u32 s11, s11, 0
	v_add_u32_e32 v157, s1, v14
	v_lshl_add_u64 v[8:9], v[8:9], 0, v[2:3]
	v_lshl_add_u64 v[20:21], s[10:11], 0, v[16:17]
	v_readfirstlane_b32 s1, v157
	v_add_u32_e32 v158, 0x2000, v157
	global_load_lds_dwordx4 v[8:9], off
	v_lshl_add_u64 v[20:21], v[20:21], 0, v[0:1]
	s_mov_b32 m0, s1
	v_readfirstlane_b32 s1, v158
	global_load_lds_dwordx4 v[20:21], off
	s_mov_b32 m0, s1
	s_add_i32 s1, s20, 0x80
	v_lshl_add_u64 v[20:21], s[10:11], 0, v[18:19]
	s_mul_hi_i32 s10, s1, 0x1600
	s_add_i32 s1, s8, 0xb0000
	s_add_u32 s1, s66, s1
	s_addc_u32 s22, s67, s10
	s_add_u32 s10, s1, s68
	s_addc_u32 s11, s22, 0
	v_add_u32_e32 v160, 0x4000, v155
	v_lshl_add_u64 v[20:21], v[20:21], 0, v[2:3]
	v_lshl_add_u64 v[16:17], s[10:11], 0, v[16:17]
	v_readfirstlane_b32 s23, v160
	global_load_lds_dwordx4 v[20:21], off
	v_lshl_add_u64 v[16:17], v[16:17], 0, v[0:1]
	s_mov_b32 m0, s23
	v_add_u32_e32 v164, 0x6000, v155
	global_load_lds_dwordx4 v[16:17], off
	v_lshl_add_u64 v[16:17], s[10:11], 0, v[18:19]
	v_readfirstlane_b32 s10, v164
	v_lshl_add_u64 v[16:17], v[16:17], 0, v[2:3]
	s_mov_b32 m0, s10
	v_ashrrev_i32_e32 v15, 8, v144
	global_load_lds_dwordx4 v[16:17], off
	v_mov_b32_e32 v21, 0
	v_mov_b64_e32 v[22:23], 0
	v_mov_b64_e32 v[24:25], 0
	v_mov_b64_e32 v[26:27], 0
	v_mov_b64_e32 v[28:29], 0
	v_mov_b64_e32 v[30:31], 0
	v_mov_b64_e32 v[32:33], 0
	v_mov_b64_e32 v[34:35], 0
	v_mov_b64_e32 v[36:37], 0
	v_mov_b64_e32 v[38:39], 0
	v_mov_b64_e32 v[40:41], 0
	v_mov_b64_e32 v[42:43], 0
	v_mov_b64_e32 v[44:45], 0
	v_mov_b64_e32 v[46:47], 0
	v_mov_b64_e32 v[48:49], 0
	v_mov_b64_e32 v[50:51], 0
	v_mov_b64_e32 v[52:53], 0
	v_mov_b64_e32 v[54:55], 0
	v_mov_b64_e32 v[56:57], 0
	v_mov_b64_e32 v[58:59], 0
	v_mov_b64_e32 v[60:61], 0
	v_mov_b64_e32 v[62:63], 0
	v_mov_b64_e32 v[64:65], 0
	v_mov_b64_e32 v[66:67], 0
	v_mov_b64_e32 v[68:69], 0
	v_mov_b64_e32 v[70:71], 0
	v_mov_b64_e32 v[72:73], 0
	v_mov_b64_e32 v[74:75], 0
	v_mov_b64_e32 v[76:77], 0
	v_mov_b64_e32 v[78:79], 0
	v_mov_b64_e32 v[80:81], 0
	v_mov_b64_e32 v[82:83], 0
	v_mov_b64_e32 v[84:85], 0
	v_mov_b64_e32 v[86:87], 0
	v_mov_b64_e32 v[88:89], 0
	v_mov_b64_e32 v[90:91], 0
	v_mov_b64_e32 v[92:93], 0
	v_mov_b64_e32 v[94:95], 0
	v_mov_b64_e32 v[96:97], 0
	v_mov_b64_e32 v[98:99], 0
	v_mov_b64_e32 v[100:101], 0
	v_mov_b64_e32 v[102:103], 0
	v_mov_b64_e32 v[104:105], 0
	v_mov_b64_e32 v[106:107], 0
	v_mov_b64_e32 v[108:109], 0
	v_mov_b64_e32 v[110:111], 0
	v_mov_b64_e32 v[112:113], 0
	v_mov_b64_e32 v[114:115], 0
	v_mov_b64_e32 v[116:117], 0
	v_mov_b64_e32 v[118:119], 0
	v_mov_b64_e32 v[120:121], 0
	v_mov_b64_e32 v[122:123], 0
	v_mov_b64_e32 v[124:125], 0
	v_mov_b64_e32 v[126:127], 0
	v_not_b32_e32 v162, 31
	v_not_b32_e32 v246, 63
	v_cmp_eq_u32_e32 vcc, 1, v15
	s_and_saveexec_b64 s[10:11], vcc
	s_cbranch_execz .LBB0_188
	s_barrier

.LBB0_329:
	v_ashrrev_i32_e32 v0, 31, v140
	v_lshrrev_b32_e32 v0, 26, v0
	v_add_u32_e32 v0, v140, v0
	v_ashrrev_i32_e32 v1, 6, v0
	v_bfe_i32 v0, v140, 27, 1
	v_lshlrev_b32_e32 v21, 4, v140
	v_lshrrev_b32_e32 v0, 22, v0
	v_add_u32_e32 v0, v21, v0
	v_and_b32_e32 v0, 0xfffffc00, v0
	v_sub_u32_e32 v0, v21, v0
	v_lshrrev_b32_e32 v2, 4, v0
	v_bitop3_b32 v2, v2, v0, 32 bitop3:0x6c
	v_ashrrev_i32_e32 v0, 31, v0
	v_lshrrev_b32_e32 v0, 26, v0
	v_lshlrev_b32_e32 v3, 3, v1
	v_add_u32_e32 v0, v2, v0
	v_and_b32_e32 v3, -16, v3
	v_ashrrev_i32_e32 v4, 6, v0
	v_add_u32_e32 v0, v4, v3
	v_mul_i32_i24_e32 v3, 64, v4
	v_lshlrev_b32_e32 v1, 5, v1
	v_sub_u32_e32 v2, v2, v3
	v_mov_b32_e32 v7, 1
	v_and_b32_e32 v1, 32, v1
	v_ashrrev_i16_sdwa v2, v7, sext(v2) dst_sel:DWORD dst_unused:UNUSED_PAD src0_sel:DWORD src1_sel:BYTE_0
	v_add_u32_sdwa v2, v1, sext(v2) dst_sel:DWORD dst_unused:UNUSED_PAD src0_sel:DWORD src1_sel:WORD_0
	v_add_u32_e32 v1, 0x2000, v21
	v_ashrrev_i32_e32 v3, 31, v1
	v_lshrrev_b32_e32 v3, 22, v3
	v_add_u32_e32 v3, v1, v3
	v_ashrrev_i32_e32 v3, 10, v3
	v_mul_i32_i24_e32 v4, 0x400, v3
	v_sub_u32_e32 v1, v1, v4
	v_lshrrev_b32_e32 v4, 4, v1
	v_bitop3_b32 v1, v4, v1, 32 bitop3:0x6c
	s_add_i32 s0, s0, s1
	v_ashrrev_i32_e32 v5, 31, v1
	s_mul_hi_i32 s1, s0, 0x2e8ba2e9
	v_lshrrev_b32_e32 v5, 26, v5
	s_lshr_b32 s2, s1, 31
	s_ashr_i32 s1, s1, 4
	v_add_u32_e32 v5, v1, v5
	s_add_i32 s1, s1, s2
	v_ashrrev_i32_e32 v6, 6, v5
	v_and_b32_e32 v5, 0xc0, v5
	s_lshl_b32 s6, s1, 2
	v_lshlrev_b32_e32 v4, 3, v3
	v_lshlrev_b32_e32 v3, 5, v3
	v_sub_u32_e32 v1, v1, v5
	s_sub_i32 s2, 0x42, s6
	v_and_b32_e32 v4, -16, v4
	v_and_b32_e32 v3, 32, v3
	v_ashrrev_i16_sdwa v1, v7, sext(v1) dst_sel:DWORD dst_unused:UNUSED_PAD src0_sel:DWORD src1_sel:BYTE_0
	s_min_u32 s3, s2, 4
	s_mul_i32 s2, s1, 0x58
	v_add_u32_e32 v4, v6, v4
	v_add_u32_sdwa v6, v3, sext(v1) dst_sel:DWORD dst_unused:UNUSED_PAD src0_sel:DWORD src1_sel:WORD_0
	s_sub_i32 s7, s0, s2
	v_cvt_f32_ubyte0_e32 v3, s3
	v_cvt_f32_i32_e32 v1, s7
	v_rcp_iflag_f32_e32 v5, v3
	s_ashr_i32 s4, s7, 30
	s_or_b32 s8, s4, 1
	v_ashrrev_i32_e32 v7, 31, v6
	v_mul_f32_e32 v5, v1, v5
	v_trunc_f32_e32 v5, v5
	v_fma_f32 v1, -v5, v3, v1
	v_cvt_i32_f32_e32 v5, v5
	v_cmp_ge_f32_e64 s[4:5], |v1|, v3
	s_and_b64 s[4:5], s[4:5], exec
	s_cselect_b32 s4, s8, 0
	v_readfirstlane_b32 s5, v5
	s_add_i32 s4, s5, s4
	s_mul_i32 s3, s4, s3
	s_sext_i32_i8 s14, s4
	s_sub_i32 s4, s7, s3
	s_sext_i32_i8 s4, s4
	s_lshl_b32 s8, s14, 8
	s_add_i32 s6, s6, s4
	s_ashr_i32 s9, s8, 31
	s_lshl_b32 s4, s6, 8
	s_lshl_b64 s[6:7], s[8:9], 11
	s_add_u32 s16, s12, s6
	v_readlane_b32 s5, v254, 61
	v_ashrrev_i32_e32 v1, 31, v0
	s_addc_u32 s17, s13, s7
	v_add_u32_e32 v144, s5, v21
	v_lshlrev_b64 v[0:1], 11, v[0:1]
	v_ashrrev_i32_e32 v3, 31, v2
	v_lshl_add_u64 v[8:9], s[16:17], 0, v[0:1]
	v_lshlrev_b64 v[2:3], 1, v[2:3]
	v_readfirstlane_b32 s5, v144
	v_add_u32_e32 v149, 0x2000, v144
	v_lshl_add_u64 v[8:9], v[8:9], 0, v[2:3]
	s_mov_b32 m0, s5
	v_ashrrev_i32_e32 v5, 31, v4
	v_readfirstlane_b32 s5, v149
	global_load_lds_dwordx4 v[8:9], off
	v_lshlrev_b64 v[4:5], 11, v[4:5]
	s_mov_b32 m0, s5
	s_ashr_i32 s5, s4, 31
	v_lshl_add_u64 v[10:11], s[16:17], 0, v[4:5]
	s_lshl_b64 s[16:17], s[4:5], 11
	s_add_u32 s16, s44, s16
	s_addc_u32 s17, s45, s17
	s_bitset1_b32 s8, 7
	s_ashr_i32 s9, s8, 31
	s_lshl_b64 s[8:9], s[8:9], 11
	v_lshlrev_b64 v[6:7], 1, v[6:7]
	v_add_u32_e32 v150, 0, v21
	s_add_u32 s8, s12, s8
	v_lshl_add_u64 v[10:11], v[10:11], 0, v[6:7]
	v_lshl_add_u64 v[12:13], s[16:17], 0, v[0:1]
	v_readfirstlane_b32 s5, v150
	v_add_u32_e32 v151, 0x2000, v150
	s_addc_u32 s9, s13, s9
	global_load_lds_dwordx4 v[10:11], off
	v_lshl_add_u64 v[12:13], v[12:13], 0, v[2:3]
	s_mov_b32 m0, s5
	v_readfirstlane_b32 s5, v151
	v_lshl_add_u64 v[16:17], s[8:9], 0, v[0:1]
	v_lshl_add_u64 v[18:19], s[8:9], 0, v[4:5]
	s_or_b32 s8, s4, 0x80
	global_load_lds_dwordx4 v[12:13], off
	s_mov_b32 m0, s5
	v_readlane_b32 s5, v254, 62
	s_ashr_i32 s9, s8, 31
	v_lshl_add_u64 v[14:15], s[16:17], 0, v[4:5]
	v_add_u32_e32 v153, s5, v21
	s_lshl_b64 s[8:9], s[8:9], 11
	v_lshl_add_u64 v[14:15], v[14:15], 0, v[6:7]
	v_readfirstlane_b32 s5, v153
	v_add_u32_e32 v154, 0x2000, v153
	s_add_u32 s8, s44, s8
	global_load_lds_dwordx4 v[14:15], off
	v_lshl_add_u64 v[16:17], v[16:17], 0, v[2:3]
	s_mov_b32 m0, s5
	v_readfirstlane_b32 s5, v154
	s_addc_u32 s9, s45, s9
	v_add_u32_e32 v155, 0x4000, v150
	global_load_lds_dwordx4 v[16:17], off
	v_lshl_add_u64 v[18:19], v[18:19], 0, v[6:7]
	s_mov_b32 m0, s5
	v_lshl_add_u64 v[22:23], s[8:9], 0, v[0:1]
	v_readfirstlane_b32 s5, v155
	v_add_u32_e32 v157, 0x6000, v150
	global_load_lds_dwordx4 v[18:19], off
	v_lshl_add_u64 v[128:129], v[22:23], 0, v[2:3]
	s_mov_b32 m0, s5
	v_lshl_add_u64 v[22:23], s[8:9], 0, v[4:5]
	v_readfirstlane_b32 s5, v157
	global_load_lds_dwordx4 v[128:129], off
	v_lshl_add_u64 v[130:131], v[22:23], 0, v[6:7]
	s_mov_b32 m0, s5
	v_ashrrev_i32_e32 v20, 8, v140
	global_load_lds_dwordx4 v[130:131], off
	v_mov_b32_e32 v23, 0
	v_mov_b64_e32 v[24:25], 0
	v_mov_b64_e32 v[26:27], 0
	v_mov_b64_e32 v[28:29], 0
	v_mov_b64_e32 v[30:31], 0
	v_mov_b64_e32 v[32:33], 0
	v_mov_b64_e32 v[34:35], 0
	v_mov_b64_e32 v[36:37], 0
	v_mov_b64_e32 v[38:39], 0
	v_mov_b64_e32 v[40:41], 0
	v_mov_b64_e32 v[42:43], 0
	v_mov_b64_e32 v[44:45], 0
	v_mov_b64_e32 v[46:47], 0
	v_mov_b64_e32 v[48:49], 0
	v_mov_b64_e32 v[50:51], 0
	v_mov_b64_e32 v[52:53], 0
	v_mov_b64_e32 v[54:55], 0
	v_mov_b64_e32 v[56:57], 0
	v_mov_b64_e32 v[58:59], 0
	v_mov_b64_e32 v[60:61], 0
	v_mov_b64_e32 v[62:63], 0
	v_mov_b64_e32 v[64:65], 0
	v_mov_b64_e32 v[66:67], 0
	v_mov_b64_e32 v[68:69], 0
	v_mov_b64_e32 v[70:71], 0
	v_mov_b64_e32 v[72:73], 0
	v_mov_b64_e32 v[74:75], 0
	v_mov_b64_e32 v[76:77], 0
	v_mov_b64_e32 v[78:79], 0
	v_mov_b64_e32 v[80:81], 0
	v_mov_b64_e32 v[82:83], 0
	v_mov_b64_e32 v[84:85], 0
	v_mov_b64_e32 v[86:87], 0
	v_mov_b64_e32 v[88:89], 0
	v_mov_b64_e32 v[90:91], 0
	v_mov_b64_e32 v[92:93], 0
	v_mov_b64_e32 v[94:95], 0
	v_mov_b64_e32 v[96:97], 0
	v_mov_b64_e32 v[98:99], 0
	v_mov_b64_e32 v[100:101], 0
	v_mov_b64_e32 v[102:103], 0
	v_mov_b64_e32 v[104:105], 0
	v_mov_b64_e32 v[106:107], 0
	v_mov_b64_e32 v[108:109], 0
	v_mov_b64_e32 v[110:111], 0
	v_mov_b64_e32 v[112:113], 0
	v_mov_b64_e32 v[114:115], 0
	v_mov_b64_e32 v[116:117], 0
	v_mov_b64_e32 v[118:119], 0
	v_mov_b64_e32 v[120:121], 0
	v_mov_b64_e32 v[122:123], 0
	v_mov_b64_e32 v[124:125], 0
	v_mov_b64_e32 v[126:127], 0
	v_cmp_eq_u32_e32 vcc, 1, v20
	s_and_saveexec_b64 s[8:9], vcc
	s_cbranch_execz .LBB0_331
	s_barrier

.LBB0_357:
	v_bfe_i32 v1, v144, 27, 1
	v_lshlrev_b32_e32 v24, 4, v144
	v_lshrrev_b32_e32 v1, 22, v1
	v_add_u32_e32 v1, v24, v1
	v_and_b32_e32 v1, 0xfffffc00, v1
	v_ashrrev_i32_e32 v0, 31, v144
	v_sub_u32_e32 v1, v24, v1
	v_lshrrev_b32_e32 v0, 26, v0
	v_lshrrev_b32_e32 v2, 4, v1
	v_add_u32_e32 v0, v144, v0
	v_bitop3_b32 v2, v2, v1, 32 bitop3:0x6c
	v_ashrrev_i32_e32 v1, 31, v1
	v_ashrrev_i32_e32 v0, 6, v0
	v_lshrrev_b32_e32 v1, 26, v1
	v_lshlrev_b32_e32 v3, 3, v0
	v_add_u32_e32 v1, v2, v1
	v_and_b32_e32 v3, -16, v3
	v_ashrrev_i32_e32 v1, 6, v1
	s_waitcnt vmcnt(0)
	v_add_u32_e32 v8, v1, v3
	v_mul_i32_i24_e32 v1, 64, v1
	v_lshlrev_b32_e32 v0, 5, v0
	v_sub_u32_e32 v1, v2, v1
	v_mov_b32_e32 v5, 1
	v_and_b32_e32 v0, 32, v0
	v_ashrrev_i16_sdwa v1, v5, sext(v1) dst_sel:DWORD dst_unused:UNUSED_PAD src0_sel:DWORD src1_sel:BYTE_0
	v_add_u32_sdwa v128, v0, sext(v1) dst_sel:DWORD dst_unused:UNUSED_PAD src0_sel:DWORD src1_sel:WORD_0
	v_add_u32_e32 v0, 0x2000, v24
	v_ashrrev_i32_e32 v1, 31, v0
	v_lshrrev_b32_e32 v1, 22, v1
	v_add_u32_e32 v1, v0, v1
	v_ashrrev_i32_e32 v1, 10, v1
	v_mul_i32_i24_e32 v2, 0x400, v1
	v_sub_u32_e32 v0, v0, v2
	v_lshrrev_b32_e32 v2, 4, v0
	v_bitop3_b32 v0, v2, v0, 32 bitop3:0x6c
	v_ashrrev_i32_e32 v3, 31, v0
	v_lshrrev_b32_e32 v3, 26, v3
	s_lshl_b32 s10, s1, 8
	v_lshlrev_b32_e32 v2, 3, v1
	v_add_u32_e32 v3, v0, v3
	s_ashr_i32 s11, s10, 31
	v_and_b32_e32 v2, -16, v2
	v_ashrrev_i32_e32 v4, 6, v3
	s_lshl_b64 s[12:13], s[10:11], 11
	v_add_u32_e32 v10, v4, v2
	v_and_b32_e32 v2, 0xc0, v3
	s_add_u32 s1, s26, s12
	v_lshlrev_b32_e32 v1, 5, v1
	v_sub_u32_e32 v0, v0, v2
	s_addc_u32 s3, s27, s13
	s_lshl_b32 s68, s14, 1
	v_and_b32_e32 v1, 32, v1
	v_ashrrev_i16_sdwa v0, v5, sext(v0) dst_sel:DWORD dst_unused:UNUSED_PAD src0_sel:DWORD src1_sel:BYTE_0
	s_add_u32 s2, s1, s68
	v_readlane_b32 s1, v254, 61
	v_ashrrev_i32_e32 v9, 31, v8
	v_add_u32_sdwa v130, v1, sext(v0) dst_sel:DWORD dst_unused:UNUSED_PAD src0_sel:DWORD src1_sel:WORD_0
	s_addc_u32 s3, s3, 0
	v_add_u32_e32 v152, s1, v24
	v_lshlrev_b64 v[0:1], 11, v[8:9]
	v_ashrrev_i32_e32 v129, 31, v128
	v_lshl_add_u64 v[4:5], s[2:3], 0, v[0:1]
	v_lshlrev_b64 v[2:3], 1, v[128:129]
	v_readfirstlane_b32 s1, v152
	v_add_u32_e32 v153, 0x2000, v152
	s_ashr_i32 s5, s4, 31
	v_lshl_add_u64 v[12:13], v[4:5], 0, v[2:3]
	s_mov_b32 m0, s1
	v_readfirstlane_b32 s1, v153
	s_lshl_b64 s[14:15], s[4:5], 11
	global_load_lds_dwordx4 v[12:13], off
	v_ashrrev_i32_e32 v11, 31, v10
	s_mov_b32 m0, s1
	s_add_u32 s1, s44, s14
	v_lshlrev_b64 v[4:5], 11, v[10:11]
	s_addc_u32 s5, s45, s15
	v_lshl_add_u64 v[14:15], s[2:3], 0, v[4:5]
	v_ashrrev_i32_e32 v131, 31, v130
	s_add_u32 s2, s1, s68
	v_lshlrev_b64 v[6:7], 1, v[130:131]
	s_addc_u32 s3, s5, 0
	v_add_u32_e32 v155, 0, v24
	v_lshl_add_u64 v[14:15], v[14:15], 0, v[6:7]
	v_lshl_add_u64 v[16:17], s[2:3], 0, v[0:1]
	v_readfirstlane_b32 s11, v155
	v_add_u32_e32 v156, 0x2000, v155
	global_load_lds_dwordx4 v[14:15], off
	v_lshl_add_u64 v[16:17], v[16:17], 0, v[2:3]
	s_mov_b32 m0, s11
	v_lshl_add_u64 v[18:19], s[2:3], 0, v[4:5]
	v_readfirstlane_b32 s2, v156
	global_load_lds_dwordx4 v[16:17], off
	s_mov_b32 m0, s2
	s_or_b32 s2, s10, 0x80
	s_ashr_i32 s3, s2, 31
	s_lshl_b64 s[2:3], s[2:3], 11
	s_add_u32 s2, s26, s2
	s_addc_u32 s3, s27, s3
	s_add_u32 s2, s2, s68
	v_readlane_b32 s11, v254, 62
	s_addc_u32 s3, s3, 0
	v_lshl_add_u64 v[18:19], v[18:19], 0, v[6:7]
	v_add_u32_e32 v158, s11, v24
	v_lshl_add_u64 v[20:21], s[2:3], 0, v[0:1]
	v_readfirstlane_b32 s11, v158
	v_add_u32_e32 v159, 0x2000, v158
	s_add_u32 s1, s1, 0x40000
	global_load_lds_dwordx4 v[18:19], off
	v_lshl_add_u64 v[20:21], v[20:21], 0, v[2:3]
	s_mov_b32 m0, s11
	v_lshl_add_u64 v[22:23], s[2:3], 0, v[4:5]
	v_readfirstlane_b32 s2, v159
	s_addc_u32 s5, s5, 0
	global_load_lds_dwordx4 v[20:21], off
	s_mov_b32 m0, s2
	s_add_u32 s2, s1, s68
	s_addc_u32 s3, s5, 0
	v_add_u32_e32 v160, 0x4000, v155
	v_lshl_add_u64 v[22:23], v[22:23], 0, v[6:7]
	v_lshl_add_u64 v[26:27], s[2:3], 0, v[0:1]
	v_readfirstlane_b32 s11, v160
	global_load_lds_dwordx4 v[22:23], off
	v_lshl_add_u64 v[26:27], v[26:27], 0, v[2:3]
	s_mov_b32 m0, s11
	v_add_u32_e32 v164, 0x6000, v155
	global_load_lds_dwordx4 v[26:27], off
	v_lshl_add_u64 v[26:27], s[2:3], 0, v[4:5]
	v_readfirstlane_b32 s2, v164
	v_lshl_add_u64 v[26:27], v[26:27], 0, v[6:7]
	s_mov_b32 m0, s2
	v_ashrrev_i32_e32 v25, 8, v144
	global_load_lds_dwordx4 v[26:27], off
	v_mov_b64_e32 v[26:27], 0
	v_mov_b64_e32 v[28:29], 0
	v_mov_b64_e32 v[30:31], 0
	v_mov_b64_e32 v[32:33], 0
	v_mov_b64_e32 v[34:35], 0
	v_mov_b64_e32 v[36:37], 0
	v_mov_b64_e32 v[38:39], 0
	v_mov_b64_e32 v[40:41], 0
	v_mov_b64_e32 v[42:43], 0
	v_mov_b64_e32 v[44:45], 0
	v_mov_b64_e32 v[46:47], 0
	v_mov_b64_e32 v[48:49], 0
	v_mov_b64_e32 v[50:51], 0
	v_mov_b64_e32 v[52:53], 0
	v_mov_b64_e32 v[54:55], 0
	v_mov_b64_e32 v[56:57], 0
	v_mov_b64_e32 v[58:59], 0
	v_mov_b64_e32 v[60:61], 0
	v_mov_b64_e32 v[62:63], 0
	v_mov_b64_e32 v[64:65], 0
	v_mov_b64_e32 v[66:67], 0
	v_mov_b64_e32 v[68:69], 0
	v_mov_b64_e32 v[70:71], 0
	v_mov_b64_e32 v[72:73], 0
	v_mov_b64_e32 v[74:75], 0
	v_mov_b64_e32 v[76:77], 0
	v_mov_b64_e32 v[78:79], 0
	v_mov_b64_e32 v[80:81], 0
	v_mov_b64_e32 v[82:83], 0
	v_mov_b64_e32 v[84:85], 0
	v_mov_b64_e32 v[86:87], 0
	v_mov_b64_e32 v[88:89], 0
	v_mov_b64_e32 v[90:91], 0
	v_mov_b64_e32 v[92:93], 0
	v_mov_b64_e32 v[94:95], 0
	v_mov_b64_e32 v[96:97], 0
	v_mov_b64_e32 v[98:99], 0
	v_mov_b64_e32 v[100:101], 0
	v_mov_b64_e32 v[102:103], 0
	v_mov_b64_e32 v[104:105], 0
	v_mov_b64_e32 v[106:107], 0
	v_mov_b64_e32 v[108:109], 0
	v_mov_b64_e32 v[110:111], 0
	v_mov_b64_e32 v[112:113], 0
	v_mov_b64_e32 v[114:115], 0
	v_mov_b64_e32 v[116:117], 0
	v_mov_b64_e32 v[118:119], 0
	v_mov_b64_e32 v[120:121], 0
	v_mov_b64_e32 v[122:123], 0
	v_mov_b64_e32 v[124:125], 0
	v_mov_b64_e32 v[126:127], 0
	v_not_b32_e32 v246, 63
	v_cmp_eq_u32_e32 vcc, 1, v25
	s_and_saveexec_b64 s[20:21], vcc
	s_cbranch_execz .LBB0_359
	s_barrier

.LBB0_1290:
	v_ashrrev_i32_e32 v0, 31, v140
	v_lshrrev_b32_e32 v0, 26, v0
	v_add_u32_e32 v0, v140, v0
	v_ashrrev_i32_e32 v1, 6, v0
	v_bfe_i32 v0, v140, 27, 1
	v_lshlrev_b32_e32 v20, 4, v140
	v_lshrrev_b32_e32 v0, 22, v0
	v_add_u32_e32 v0, v20, v0
	v_and_b32_e32 v0, 0xfffffc00, v0
	v_sub_u32_e32 v0, v20, v0
	v_lshrrev_b32_e32 v2, 4, v0
	v_bitop3_b32 v2, v2, v0, 32 bitop3:0x6c
	v_ashrrev_i32_e32 v0, 31, v0
	v_lshrrev_b32_e32 v0, 26, v0
	v_lshlrev_b32_e32 v3, 3, v1
	v_add_u32_e32 v0, v2, v0
	v_and_b32_e32 v3, -16, v3
	s_waitcnt vmcnt(0)
	v_ashrrev_i32_e32 v4, 6, v0
	v_add_u32_e32 v0, v4, v3
	v_mul_i32_i24_e32 v3, 64, v4
	v_lshlrev_b32_e32 v1, 5, v1
	v_sub_u32_e32 v2, v2, v3
	v_mov_b32_e32 v7, 1
	v_and_b32_e32 v1, 32, v1
	v_ashrrev_i16_sdwa v2, v7, sext(v2) dst_sel:DWORD dst_unused:UNUSED_PAD src0_sel:DWORD src1_sel:BYTE_0
	v_add_u32_sdwa v2, v1, sext(v2) dst_sel:DWORD dst_unused:UNUSED_PAD src0_sel:DWORD src1_sel:WORD_0
	v_add_u32_e32 v1, 0x2000, v20
	v_ashrrev_i32_e32 v3, 31, v1
	v_lshrrev_b32_e32 v3, 22, v3
	v_add_u32_e32 v3, v1, v3
	v_ashrrev_i32_e32 v3, 10, v3
	v_mul_i32_i24_e32 v4, 0x400, v3
	v_sub_u32_e32 v1, v1, v4
	v_lshrrev_b32_e32 v4, 4, v1
	s_add_i32 s1, s0, s1
	v_bitop3_b32 v1, v4, v1, 32 bitop3:0x6c
	s_mul_hi_i32 s0, s1, 0x78787879
	v_ashrrev_i32_e32 v5, 31, v1
	s_lshr_b32 s2, s0, 31
	s_ashr_i32 s0, s0, 5
	v_lshrrev_b32_e32 v5, 26, v5
	s_add_i32 s2, s0, s2
	v_add_u32_e32 v5, v1, v5
	s_lshl_b32 s6, s2, 2
	v_ashrrev_i32_e32 v6, 6, v5
	v_and_b32_e32 v5, 0xc0, v5
	s_sub_i32 s0, 0x42, s6
	v_sub_u32_e32 v1, v1, v5
	s_min_u32 s7, s0, 4
	s_mul_i32 s3, s2, 0x44
	v_ashrrev_i16_sdwa v1, v7, sext(v1) dst_sel:DWORD dst_unused:UNUSED_PAD src0_sel:DWORD src1_sel:BYTE_0
	s_sub_i32 s14, s1, s3
	v_cvt_f32_ubyte0_e32 v7, s7
	v_cvt_f32_i32_e32 v5, s14
	v_rcp_iflag_f32_e32 v8, v7
	v_lshlrev_b32_e32 v4, 3, v3
	v_lshlrev_b32_e32 v3, 5, v3
	v_and_b32_e32 v4, -16, v4
	v_and_b32_e32 v3, 32, v3
	v_add_u32_e32 v4, v6, v4
	v_add_u32_sdwa v6, v3, sext(v1) dst_sel:DWORD dst_unused:UNUSED_PAD src0_sel:DWORD src1_sel:WORD_0
	v_mul_f32_e32 v1, v5, v8
	v_trunc_f32_e32 v1, v1
	v_fma_f32 v3, -v1, v7, v5
	v_cvt_i32_f32_e32 v1, v1
	s_ashr_i32 s0, s14, 30
	s_or_b32 s0, s0, 1
	v_cmp_ge_f32_e64 s[4:5], |v3|, v7
	s_and_b64 s[4:5], s[4:5], exec
	s_cselect_b32 s0, s0, 0
	v_readfirstlane_b32 s4, v1
	s_add_i32 s0, s4, s0
	s_mul_i32 s22, s0, s7
	s_sext_i32_i8 s4, s0
	s_sub_i32 s5, s14, s22
	s_sext_i32_i8 s5, s5
	s_lshl_b32 s4, s4, 8
	s_add_i32 s6, s6, s5
	s_ashr_i32 s5, s4, 31
	s_lshl_b32 s6, s6, 8
	s_lshl_b64 s[14:15], s[4:5], 11
	s_add_u32 s18, s46, s14
	v_ashrrev_i32_e32 v1, 31, v0
	v_ashrrev_i32_e32 v5, 31, v4
	s_addc_u32 s19, s47, s15
	v_lshlrev_b64 v[0:1], 11, v[0:1]
	v_lshlrev_b64 v[4:5], 11, v[4:5]
	s_ashr_i32 s7, s6, 31
	v_lshl_add_u64 v[8:9], s[18:19], 0, v[0:1]
	v_lshl_add_u64 v[10:11], s[18:19], 0, v[4:5]
	s_lshl_b64 s[18:19], s[6:7], 11
	s_add_u32 s18, s44, s18
	s_addc_u32 s19, s45, s19
	v_readlane_b32 s5, v254, 61
	v_lshl_add_u64 v[12:13], s[18:19], 0, v[0:1]
	v_lshl_add_u64 v[14:15], s[18:19], 0, v[4:5]
	s_or_b32 s18, s4, 0x80
	v_add_u32_e32 v144, s5, v20
	v_ashrrev_i32_e32 v3, 31, v2
	s_ashr_i32 s19, s18, 31
	v_lshlrev_b64 v[2:3], 1, v[2:3]
	v_readfirstlane_b32 s5, v144
	v_ashrrev_i32_e32 v7, 31, v6
	v_add_u32_e32 v149, 0x2000, v144
	s_lshl_b64 s[18:19], s[18:19], 11
	v_lshl_add_u64 v[8:9], v[8:9], 0, v[2:3]
	s_mov_b32 m0, s5
	v_lshlrev_b64 v[6:7], 1, v[6:7]
	v_readfirstlane_b32 s5, v149
	v_add_u32_e32 v150, 0, v20
	s_add_u32 s18, s46, s18
	global_load_lds_dwordx4 v[8:9], off
	v_lshl_add_u64 v[10:11], v[10:11], 0, v[6:7]
	s_mov_b32 m0, s5
	v_readfirstlane_b32 s5, v150
	v_add_u32_e32 v151, 0x2000, v150
	s_addc_u32 s19, s47, s19
	global_load_lds_dwordx4 v[10:11], off
	v_lshl_add_u64 v[12:13], v[12:13], 0, v[2:3]
	s_mov_b32 m0, s5
	v_readfirstlane_b32 s5, v151
	v_lshl_add_u64 v[16:17], s[18:19], 0, v[0:1]
	v_lshl_add_u64 v[18:19], s[18:19], 0, v[4:5]
	s_or_b32 s18, s6, 0x80
	global_load_lds_dwordx4 v[12:13], off
	s_mov_b32 m0, s5
	v_readlane_b32 s5, v254, 62
	s_ashr_i32 s19, s18, 31
	s_lshl_b64 s[18:19], s[18:19], 11
	v_add_u32_e32 v153, s5, v20
	v_lshl_add_u64 v[14:15], v[14:15], 0, v[6:7]
	v_readfirstlane_b32 s5, v153
	v_add_u32_e32 v154, 0x2000, v153
	s_add_u32 s18, s44, s18
	global_load_lds_dwordx4 v[14:15], off
	v_lshl_add_u64 v[16:17], v[16:17], 0, v[2:3]
	s_mov_b32 m0, s5
	v_readfirstlane_b32 s5, v154
	s_addc_u32 s19, s45, s19
	v_add_u32_e32 v156, 0x4000, v150
	global_load_lds_dwordx4 v[16:17], off
	v_lshl_add_u64 v[18:19], v[18:19], 0, v[6:7]
	s_mov_b32 m0, s5
	v_lshl_add_u64 v[22:23], s[18:19], 0, v[0:1]
	v_readfirstlane_b32 s5, v156
	v_add_u32_e32 v157, 0x6000, v150
	global_load_lds_dwordx4 v[18:19], off
	v_lshl_add_u64 v[128:129], v[22:23], 0, v[2:3]
	s_mov_b32 m0, s5
	v_lshl_add_u64 v[22:23], s[18:19], 0, v[4:5]
	v_readfirstlane_b32 s5, v157
	global_load_lds_dwordx4 v[128:129], off
	v_lshl_add_u64 v[130:131], v[22:23], 0, v[6:7]
	s_mov_b32 m0, s5
	v_ashrrev_i32_e32 v21, 8, v140
	global_load_lds_dwordx4 v[130:131], off
	v_mov_b32_e32 v23, 0
	v_mov_b64_e32 v[24:25], 0
	v_mov_b64_e32 v[26:27], 0
	v_mov_b64_e32 v[28:29], 0
	v_mov_b64_e32 v[30:31], 0
	v_mov_b64_e32 v[32:33], 0
	v_mov_b64_e32 v[34:35], 0
	v_mov_b64_e32 v[36:37], 0
	v_mov_b64_e32 v[38:39], 0
	v_mov_b64_e32 v[40:41], 0
	v_mov_b64_e32 v[42:43], 0
	v_mov_b64_e32 v[44:45], 0
	v_mov_b64_e32 v[46:47], 0
	v_mov_b64_e32 v[48:49], 0
	v_mov_b64_e32 v[50:51], 0
	v_mov_b64_e32 v[52:53], 0
	v_mov_b64_e32 v[54:55], 0
	v_mov_b64_e32 v[56:57], 0
	v_mov_b64_e32 v[58:59], 0
	v_mov_b64_e32 v[60:61], 0
	v_mov_b64_e32 v[62:63], 0
	v_mov_b64_e32 v[64:65], 0
	v_mov_b64_e32 v[66:67], 0
	v_mov_b64_e32 v[68:69], 0
	v_mov_b64_e32 v[70:71], 0
	v_mov_b64_e32 v[72:73], 0
	v_mov_b64_e32 v[74:75], 0
	v_mov_b64_e32 v[76:77], 0
	v_mov_b64_e32 v[78:79], 0
	v_mov_b64_e32 v[80:81], 0
	v_mov_b64_e32 v[82:83], 0
	v_mov_b64_e32 v[84:85], 0
	v_mov_b64_e32 v[86:87], 0
	v_mov_b64_e32 v[88:89], 0
	v_mov_b64_e32 v[90:91], 0
	v_mov_b64_e32 v[92:93], 0
	v_mov_b64_e32 v[94:95], 0
	v_mov_b64_e32 v[96:97], 0
	v_mov_b64_e32 v[98:99], 0
	v_mov_b64_e32 v[100:101], 0
	v_mov_b64_e32 v[102:103], 0
	v_mov_b64_e32 v[104:105], 0
	v_mov_b64_e32 v[106:107], 0
	v_mov_b64_e32 v[108:109], 0
	v_mov_b64_e32 v[110:111], 0
	v_mov_b64_e32 v[112:113], 0
	v_mov_b64_e32 v[114:115], 0
	v_mov_b64_e32 v[116:117], 0
	v_mov_b64_e32 v[118:119], 0
	v_mov_b64_e32 v[120:121], 0
	v_mov_b64_e32 v[122:123], 0
	v_mov_b64_e32 v[124:125], 0
	v_mov_b64_e32 v[126:127], 0
	v_mov_b32_e32 v245, 0x7fc00000
	v_not_b32_e32 v246, 31
	v_not_b32_e32 v244, 63
	v_cmp_eq_u32_e32 vcc, 1, v21
	s_and_saveexec_b64 s[18:19], vcc
	s_cbranch_execz .LBB0_1292
	s_barrier
